# up-GEMM pre-step (rstd tables of the workgroup's 6 units): all ss2 loads issued first with one wait instead of 6 serialized load-wait-reduce round trips
# speedup vs baseline: 1.0020x; 1.0020x over previous
.LBB0_1116:
	s_mul_i32 s0, s88, 6
	s_mul_hi_i32 s1, s88, 6
	s_add_u32 s0, s0, s2
	s_addc_u32 s1, s1, s3
	v_mov_b64_e32 v[2:3], 0x595
	v_cmp_gt_i64_e64 s[40:41], s[0:1], v[2:3]
	v_mov_b64_e32 v[2:3], 0x596
	s_cmpk_lt_i32 s2, 0x596
	v_cmp_lt_i64_e64 s[10:11], s[0:1], v[2:3]
	s_cselect_b64 s[4:5], -1, 0
	s_lshr_b32 s0, s3, 29
	s_add_i32 s0, s2, s0
	s_ashr_i32 s51, s0, 3
	s_and_b32 s0, s0, -8
	s_sub_i32 s52, s2, s0
	s_cmp_lt_i32 s52, 6
	s_mul_i32 s14, s52, 0xb2
	s_cselect_b64 s[8:9], -1, 0
	s_add_i32 s14, s14, 6
	s_mul_i32 s15, s52, 0xb3
	v_writelane_b32 v251, s10, 4
	s_and_b64 vcc, exec, s[10:11]
	s_waitcnt lgkmcnt(0)
	v_writelane_b32 v251, s11, 5
	s_cbranch_vccnz .LBB0_1151
	v_mov_b32_e32 v2, v218
	s_movk_i32 s0, 0x100
	s_nop 0
	v_cmp_gt_i32_e32 vcc, s0, v2
	s_and_saveexec_b64 s[0:1], vcc
	s_cbranch_execz .LBB0_1150
	s_mov_b32 s98, 0
	s_add_i32 s10, 0, 0x22000
	v_lshl_add_u32 v1, v2, 2, s10
	s_andn2_b64 vcc, exec, s[4:5]
	v_add_u32_e32 v4, -2, v2
	s_cbranch_vccnz .LBB0_1120
	s_and_b64 s[10:11], s[8:9], exec
	s_cselect_b32 s10, s15, s14
	s_add_i32 s10, s10, s51
	s_mul_hi_i32 s11, s10, 0x2e8ba2e9
	s_lshr_b32 s12, s11, 31
	s_ashr_i32 s11, s11, 3
	s_add_i32 s11, s11, s12
	s_lshl_b32 s12, s11, 1
	s_sub_i32 s13, 0x41, s12
	s_min_i32 s13, s13, 2
	s_abs_i32 s13, s13
	v_cvt_f32_u32_e32 v2, s13
	s_sub_i32 s16, 0, s13
	s_mul_i32 s11, s11, 44
	s_sub_i32 s10, s10, s11
	v_rcp_iflag_f32_e32 v2, v2
	s_ashr_i32 s11, s10, 31
	s_abs_i32 s10, s10
	v_mov_b32_e32 v3, 0x3fff
	v_mul_f32_e32 v2, 0x4f7ffffe, v2
	v_cvt_u32_f32_e32 v2, v2
	s_nop 0
	v_readfirstlane_b32 s17, v2
	s_mul_i32 s16, s16, s17
	s_mul_hi_u32 s16, s17, s16
	s_add_i32 s17, s17, s16
	s_mul_hi_u32 s16, s10, s17
	s_mul_i32 s16, s16, s13
	s_sub_i32 s10, s10, s16
	s_sub_i32 s16, s10, s13
	s_cmp_ge_u32 s10, s13
	s_cselect_b32 s10, s16, s10
	s_sub_i32 s16, s10, s13
	s_cmp_ge_u32 s10, s13
	s_cselect_b32 s10, s16, s10
	s_xor_b32 s10, s10, s11
	s_sub_i32 s10, s10, s11
	s_add_i32 s10, s12, s10
	s_mulk_i32 s10, 0xfe
	v_add_u32_e32 v2, s10, v4
	v_med3_i32 v2, v2, 0, v3
	v_lshlrev_b32_e32 v2, 6, v2
	global_load_dwordx4 v[100:103], v2, s[66:67]
	global_load_dwordx4 v[104:107], v2, s[66:67] offset:16
	global_load_dwordx4 v[108:111], v2, s[66:67] offset:32
	global_load_dwordx4 v[112:115], v2, s[66:67] offset:48
	v_readlane_b32 s16, v251, 2
	v_readlane_b32 s17, v251, 3
	s_or_b32 s98, s98, 1

.LBB0_1125:
	s_add_i32 s12, s18, s12
	s_mul_hi_i32 s13, s12, 0x2e8ba2e9
	s_lshr_b32 s16, s13, 31
	s_ashr_i32 s13, s13, 3
	s_add_i32 s13, s13, s16
	s_lshl_b32 s16, s13, 1
	s_sub_i32 s17, 0x41, s16
	s_min_i32 s17, s17, 2
	s_abs_i32 s17, s17
	v_cvt_f32_u32_e32 v5, s17
	s_sub_i32 s18, 0, s17
	s_mul_i32 s13, s13, 44
	s_sub_i32 s12, s12, s13
	v_rcp_iflag_f32_e32 v5, v5
	s_ashr_i32 s13, s12, 31
	s_abs_i32 s12, s12
	v_mov_b32_e32 v6, 0x3fff
	v_mul_f32_e32 v5, 0x4f7ffffe, v5
	v_cvt_u32_f32_e32 v5, v5
	s_nop 0
	v_readfirstlane_b32 s19, v5
	s_mul_i32 s18, s18, s19
	s_mul_hi_u32 s18, s19, s18
	s_add_i32 s19, s19, s18
	s_mul_hi_u32 s18, s12, s19
	s_mul_i32 s18, s18, s17
	s_sub_i32 s12, s12, s18
	s_sub_i32 s18, s12, s17
	s_cmp_ge_u32 s12, s17
	s_cselect_b32 s12, s18, s12
	s_sub_i32 s18, s12, s17
	s_cmp_ge_u32 s12, s17
	s_cselect_b32 s12, s18, s12
	s_xor_b32 s12, s12, s13
	s_sub_i32 s12, s12, s13
	s_add_i32 s12, s16, s12
	s_mulk_i32 s12, 0xfe
	v_add_u32_e32 v5, s12, v4
	v_med3_i32 v5, v5, 0, v6
	v_lshlrev_b32_e32 v5, 6, v5
	global_load_dwordx4 v[116:119], v5, s[66:67]
	global_load_dwordx4 v[120:123], v5, s[66:67] offset:16
	global_load_dwordx4 v[124:127], v5, s[66:67] offset:32
	global_load_dwordx4 v[128:131], v5, s[66:67] offset:48
	v_readlane_b32 s18, v251, 58
	v_readlane_b32 s16, v251, 2
	v_readlane_b32 s19, v251, 59
	v_readlane_b32 s17, v251, 3
	s_or_b32 s98, s98, 2

.LBB0_1131:
	s_add_i32 s12, s18, s12
	s_mul_hi_i32 s13, s12, 0x2e8ba2e9
	s_lshr_b32 s16, s13, 31
	s_ashr_i32 s13, s13, 3
	s_add_i32 s13, s13, s16
	s_lshl_b32 s16, s13, 1
	s_sub_i32 s17, 0x41, s16
	s_min_i32 s17, s17, 2
	s_abs_i32 s17, s17
	v_cvt_f32_u32_e32 v2, s17
	s_sub_i32 s18, 0, s17
	s_mul_i32 s13, s13, 44
	s_sub_i32 s12, s12, s13
	v_rcp_iflag_f32_e32 v2, v2
	s_ashr_i32 s13, s12, 31
	s_abs_i32 s12, s12
	v_mov_b32_e32 v3, 0x3fff
	v_mul_f32_e32 v2, 0x4f7ffffe, v2
	v_cvt_u32_f32_e32 v2, v2
	s_nop 0
	v_readfirstlane_b32 s19, v2
	s_mul_i32 s18, s18, s19
	s_mul_hi_u32 s18, s19, s18
	s_add_i32 s19, s19, s18
	s_mul_hi_u32 s18, s12, s19
	s_mul_i32 s18, s18, s17
	s_sub_i32 s12, s12, s18
	s_sub_i32 s18, s12, s17
	s_cmp_ge_u32 s12, s17
	s_cselect_b32 s12, s18, s12
	s_sub_i32 s18, s12, s17
	s_cmp_ge_u32 s12, s17
	s_cselect_b32 s12, s18, s12
	s_xor_b32 s12, s12, s13
	s_sub_i32 s12, s12, s13
	s_add_i32 s12, s16, s12
	s_mulk_i32 s12, 0xfe
	v_add_u32_e32 v2, s12, v4
	v_med3_i32 v2, v2, 0, v3
	v_lshlrev_b32_e32 v2, 6, v2
	global_load_dwordx4 v[132:135], v2, s[66:67]
	global_load_dwordx4 v[136:139], v2, s[66:67] offset:16
	global_load_dwordx4 v[140:143], v2, s[66:67] offset:32
	global_load_dwordx4 v[144:147], v2, s[66:67] offset:48
	v_readlane_b32 s18, v251, 58
	v_readlane_b32 s16, v251, 2
	v_readlane_b32 s19, v251, 59
	v_readlane_b32 s17, v251, 3
	s_or_b32 s98, s98, 4

.LBB0_1137:
	s_add_i32 s12, s18, s12
	s_mul_hi_i32 s13, s12, 0x2e8ba2e9
	s_lshr_b32 s16, s13, 31
	s_ashr_i32 s13, s13, 3
	s_add_i32 s13, s13, s16
	s_lshl_b32 s16, s13, 1
	s_sub_i32 s17, 0x41, s16
	s_min_i32 s17, s17, 2
	s_abs_i32 s17, s17
	v_cvt_f32_u32_e32 v5, s17
	s_sub_i32 s18, 0, s17
	s_mul_i32 s13, s13, 44
	s_sub_i32 s12, s12, s13
	v_rcp_iflag_f32_e32 v5, v5
	s_ashr_i32 s13, s12, 31
	s_abs_i32 s12, s12
	v_mov_b32_e32 v6, 0x3fff
	v_mul_f32_e32 v5, 0x4f7ffffe, v5
	v_cvt_u32_f32_e32 v5, v5
	s_nop 0
	v_readfirstlane_b32 s19, v5
	s_mul_i32 s18, s18, s19
	s_mul_hi_u32 s18, s19, s18
	s_add_i32 s19, s19, s18
	s_mul_hi_u32 s18, s12, s19
	s_mul_i32 s18, s18, s17
	s_sub_i32 s12, s12, s18
	s_sub_i32 s18, s12, s17
	s_cmp_ge_u32 s12, s17
	s_cselect_b32 s12, s18, s12
	s_sub_i32 s18, s12, s17
	s_cmp_ge_u32 s12, s17
	s_cselect_b32 s12, s18, s12
	s_xor_b32 s12, s12, s13
	s_sub_i32 s12, s12, s13
	s_add_i32 s12, s16, s12
	s_mulk_i32 s12, 0xfe
	v_add_u32_e32 v5, s12, v4
	v_med3_i32 v5, v5, 0, v6
	v_lshlrev_b32_e32 v5, 6, v5
	global_load_dwordx4 v[148:151], v5, s[66:67]
	global_load_dwordx4 v[152:155], v5, s[66:67] offset:16
	global_load_dwordx4 v[156:159], v5, s[66:67] offset:32
	global_load_dwordx4 v[160:163], v5, s[66:67] offset:48
	v_readlane_b32 s18, v251, 58
	v_readlane_b32 s16, v251, 2
	v_readlane_b32 s19, v251, 59
	v_readlane_b32 s17, v251, 3
	s_or_b32 s98, s98, 8

.LBB0_1143:
	s_add_i32 s12, s18, s12
	s_mul_hi_i32 s13, s12, 0x2e8ba2e9
	s_lshr_b32 s16, s13, 31
	s_ashr_i32 s13, s13, 3
	s_add_i32 s13, s13, s16
	s_lshl_b32 s16, s13, 1
	s_sub_i32 s17, 0x41, s16
	s_min_i32 s17, s17, 2
	s_abs_i32 s17, s17
	v_cvt_f32_u32_e32 v2, s17
	s_sub_i32 s18, 0, s17
	s_mul_i32 s13, s13, 44
	s_sub_i32 s12, s12, s13
	v_rcp_iflag_f32_e32 v2, v2
	s_ashr_i32 s13, s12, 31
	s_abs_i32 s12, s12
	v_mov_b32_e32 v3, 0x3fff
	v_mul_f32_e32 v2, 0x4f7ffffe, v2
	v_cvt_u32_f32_e32 v2, v2
	s_nop 0
	v_readfirstlane_b32 s19, v2
	s_mul_i32 s18, s18, s19
	s_mul_hi_u32 s18, s19, s18
	s_add_i32 s19, s19, s18
	s_mul_hi_u32 s18, s12, s19
	s_mul_i32 s18, s18, s17
	s_sub_i32 s12, s12, s18
	s_sub_i32 s18, s12, s17
	s_cmp_ge_u32 s12, s17
	s_cselect_b32 s12, s18, s12
	s_sub_i32 s18, s12, s17
	s_cmp_ge_u32 s12, s17
	s_cselect_b32 s12, s18, s12
	s_xor_b32 s12, s12, s13
	s_sub_i32 s12, s12, s13
	s_add_i32 s12, s16, s12
	s_mulk_i32 s12, 0xfe
	v_add_u32_e32 v2, s12, v4
	v_med3_i32 v2, v2, 0, v3
	v_lshlrev_b32_e32 v2, 6, v2
	global_load_dwordx4 v[164:167], v2, s[66:67]
	global_load_dwordx4 v[168:171], v2, s[66:67] offset:16
	global_load_dwordx4 v[172:175], v2, s[66:67] offset:32
	global_load_dwordx4 v[176:179], v2, s[66:67] offset:48
	v_readlane_b32 s18, v251, 58
	v_readlane_b32 s16, v251, 2
	v_readlane_b32 s19, v251, 59
	v_readlane_b32 s17, v251, 3
	s_or_b32 s98, s98, 16

.LBB0_1149:
	s_add_i32 s10, s16, s10
	s_mul_hi_i32 s11, s10, 0x2e8ba2e9
	s_lshr_b32 s12, s11, 31
	s_ashr_i32 s11, s11, 3
	s_add_i32 s11, s11, s12
	s_lshl_b32 s12, s11, 1
	s_sub_i32 s13, 0x41, s12
	s_min_i32 s13, s13, 2
	s_abs_i32 s13, s13
	v_cvt_f32_u32_e32 v2, s13
	s_sub_i32 s16, 0, s13
	s_mul_i32 s11, s11, 44
	s_sub_i32 s10, s10, s11
	v_rcp_iflag_f32_e32 v2, v2
	s_ashr_i32 s11, s10, 31
	s_abs_i32 s10, s10
	v_mov_b32_e32 v3, 0x3fff
	v_mul_f32_e32 v2, 0x4f7ffffe, v2
	v_cvt_u32_f32_e32 v2, v2
	s_nop 0
	v_readfirstlane_b32 s17, v2
	s_mul_i32 s16, s16, s17
	s_mul_hi_u32 s16, s17, s16
	s_add_i32 s17, s17, s16
	s_mul_hi_u32 s16, s10, s17
	s_mul_i32 s16, s16, s13
	s_sub_i32 s10, s10, s16
	s_sub_i32 s16, s10, s13
	s_cmp_ge_u32 s10, s13
	s_cselect_b32 s10, s16, s10
	s_sub_i32 s16, s10, s13
	s_cmp_ge_u32 s10, s13
	s_cselect_b32 s10, s16, s10
	s_xor_b32 s10, s10, s11
	s_sub_i32 s10, s10, s11
	s_add_i32 s10, s12, s10
	s_mulk_i32 s10, 0xfe
	v_add_u32_e32 v2, s10, v4
	v_med3_i32 v2, v2, 0, v3
	v_lshlrev_b32_e32 v14, 6, v2
	global_load_dwordx4 v[180:183], v14, s[66:67]
	global_load_dwordx4 v[184:187], v14, s[66:67] offset:16
	global_load_dwordx4 v[188:191], v14, s[66:67] offset:32
	s_nop 0
	global_load_dwordx4 v[192:195], v14, s[66:67] offset:48
	v_readlane_b32 s16, v251, 2
	v_readlane_b32 s17, v251, 3
	s_or_b32 s98, s98, 32
.Lpre_pass2:
	s_waitcnt vmcnt(0)
	s_bitcmp1_b32 s98, 0
	s_cbranch_scc0 .Lpre_skip0
	v_pk_add_f32 v[196:197], v[102:103], v[106:107]
	v_pk_add_f32 v[198:199], v[100:101], v[104:105]
	v_pk_add_f32 v[200:201], v[110:111], v[114:115]
	v_pk_add_f32 v[202:203], v[108:109], v[112:113]
	v_pk_add_f32 v[196:197], v[196:197], v[200:201]
	v_pk_add_f32 v[198:199], v[198:199], v[202:203]
	s_nop 0
	v_pk_mov_b32 v[200:201], v[198:199], v[196:197] op_sel:[1,0]
	v_mov_b32_e32 v199, v197
	v_pk_add_f32 v[196:197], v[200:201], v[198:199]
	s_nop 0
	v_add_f32_e32 v196, v196, v197
	v_mov_b32_e32 v197, 0x358637bd
	v_fmac_f32_e32 v197, 0x3a800000, v196
	v_rsq_f32_e32 v196, v197
	ds_write_b32 v1, v196
.Lpre_skip0:
	s_bitcmp1_b32 s98, 1
	s_cbranch_scc0 .Lpre_skip1
	v_pk_add_f32 v[196:197], v[118:119], v[122:123]
	v_pk_add_f32 v[198:199], v[116:117], v[120:121]
	v_pk_add_f32 v[200:201], v[126:127], v[130:131]
	v_pk_add_f32 v[202:203], v[124:125], v[128:129]
	v_pk_add_f32 v[196:197], v[196:197], v[200:201]
	v_pk_add_f32 v[198:199], v[198:199], v[202:203]
	s_nop 0
	v_pk_mov_b32 v[200:201], v[198:199], v[196:197] op_sel:[1,0]
	v_mov_b32_e32 v199, v197
	v_pk_add_f32 v[196:197], v[200:201], v[198:199]
	s_nop 0
	v_add_f32_e32 v196, v196, v197
	v_mov_b32_e32 v197, 0x358637bd
	v_fmac_f32_e32 v197, 0x3a800000, v196
	v_rsq_f32_e32 v196, v197
	ds_write_b32 v1, v196 offset:1024
.Lpre_skip1:
	s_bitcmp1_b32 s98, 2
	s_cbranch_scc0 .Lpre_skip2
	v_pk_add_f32 v[196:197], v[134:135], v[138:139]
	v_pk_add_f32 v[198:199], v[132:133], v[136:137]
	v_pk_add_f32 v[200:201], v[142:143], v[146:147]
	v_pk_add_f32 v[202:203], v[140:141], v[144:145]
	v_pk_add_f32 v[196:197], v[196:197], v[200:201]
	v_pk_add_f32 v[198:199], v[198:199], v[202:203]
	s_nop 0
	v_pk_mov_b32 v[200:201], v[198:199], v[196:197] op_sel:[1,0]
	v_mov_b32_e32 v199, v197
	v_pk_add_f32 v[196:197], v[200:201], v[198:199]
	s_nop 0
	v_add_f32_e32 v196, v196, v197
	v_mov_b32_e32 v197, 0x358637bd
	v_fmac_f32_e32 v197, 0x3a800000, v196
	v_rsq_f32_e32 v196, v197
	ds_write_b32 v1, v196 offset:2048
.Lpre_skip2:
	s_bitcmp1_b32 s98, 3
	s_cbranch_scc0 .Lpre_skip3
	v_pk_add_f32 v[196:197], v[150:151], v[154:155]
	v_pk_add_f32 v[198:199], v[148:149], v[152:153]
	v_pk_add_f32 v[200:201], v[158:159], v[162:163]
	v_pk_add_f32 v[202:203], v[156:157], v[160:161]
	v_pk_add_f32 v[196:197], v[196:197], v[200:201]
	v_pk_add_f32 v[198:199], v[198:199], v[202:203]
	s_nop 0
	v_pk_mov_b32 v[200:201], v[198:199], v[196:197] op_sel:[1,0]
	v_mov_b32_e32 v199, v197
	v_pk_add_f32 v[196:197], v[200:201], v[198:199]
	s_nop 0
	v_add_f32_e32 v196, v196, v197
	v_mov_b32_e32 v197, 0x358637bd
	v_fmac_f32_e32 v197, 0x3a800000, v196
	v_rsq_f32_e32 v196, v197
	ds_write_b32 v1, v196 offset:3072
.Lpre_skip3:
	s_bitcmp1_b32 s98, 4
	s_cbranch_scc0 .Lpre_skip4
	v_pk_add_f32 v[196:197], v[166:167], v[170:171]
	v_pk_add_f32 v[198:199], v[164:165], v[168:169]
	v_pk_add_f32 v[200:201], v[174:175], v[178:179]
	v_pk_add_f32 v[202:203], v[172:173], v[176:177]
	v_pk_add_f32 v[196:197], v[196:197], v[200:201]
	v_pk_add_f32 v[198:199], v[198:199], v[202:203]
	s_nop 0
	v_pk_mov_b32 v[200:201], v[198:199], v[196:197] op_sel:[1,0]
	v_mov_b32_e32 v199, v197
	v_pk_add_f32 v[196:197], v[200:201], v[198:199]
	s_nop 0
	v_add_f32_e32 v196, v196, v197
	v_mov_b32_e32 v197, 0x358637bd
	v_fmac_f32_e32 v197, 0x3a800000, v196
	v_rsq_f32_e32 v196, v197
	ds_write_b32 v1, v196 offset:4096
.Lpre_skip4:
	s_bitcmp1_b32 s98, 5
	s_cbranch_scc0 .Lpre_skip5
	v_pk_add_f32 v[196:197], v[182:183], v[186:187]
	v_pk_add_f32 v[198:199], v[180:181], v[184:185]
	v_pk_add_f32 v[200:201], v[190:191], v[194:195]
	v_pk_add_f32 v[202:203], v[188:189], v[192:193]
	v_pk_add_f32 v[196:197], v[196:197], v[200:201]
	v_pk_add_f32 v[198:199], v[198:199], v[202:203]
	s_nop 0
	v_pk_mov_b32 v[200:201], v[198:199], v[196:197] op_sel:[1,0]
	v_mov_b32_e32 v199, v197
	v_pk_add_f32 v[196:197], v[200:201], v[198:199]
	s_nop 0
	v_add_f32_e32 v196, v196, v197
	v_mov_b32_e32 v197, 0x358637bd
	v_fmac_f32_e32 v197, 0x3a800000, v196
	v_rsq_f32_e32 v196, v197
	ds_write_b32 v1, v196 offset:5120
.Lpre_skip5:
.LBB0_1150:
	s_or_b64 exec, exec, s[0:1]
	s_waitcnt vmcnt(0) lgkmcnt(0)
	s_barrier
